# v047 + odd-wave-slot copy of the A loop with QK burst priority 2 + one-time 768-cycle stagger of workgroups 32..63 at the start of the GEMM phases
# speedup vs baseline: 1.0020x; 1.0020x over previous
; __global__ void __launch_bounds__(256, 2) hymba_mega(Params p) {
;     ...
;   for (int layer = 0; layer < DEPTH; ++layer) {
;     for (int rep = 0; rep < REP_G0; ++rep) {
;       for (int u = lb; u < 8 * 26; u += nxb) gemm_tile<0>(p, layer, xcd + 8 * (u & 7), u >> 3, sm, wv);
.LBB0_109:
	s_mov_b32 s40, 0
	v_readlane_b32 s0, v250, 1
	v_readlane_b32 s1, v250, 2
	s_mov_b64 s[44:45], s[20:21]
	s_andn2_b64 vcc, exec, s[0:1]
	s_cbranch_vccnz .LBB0_141
	v_readlane_b32 s2, v250, 23
	s_cmp_lt_u32 s2, 32
	s_cbranch_scc1 .Lstag_i
	s_sleep 12
.Lstag_i:
	v_readlane_b32 s2, v250, 26
	s_mul_i32 s0, s2, 0x680000
	v_readlane_b32 s3, v250, 27
	s_add_u32 s16, s56, s0
	s_mov_b32 s0, s2
	s_mov_b32 s3, s25
	v_writelane_b32 v250, s0, 26
	s_addc_u32 s17, s57, 0
	s_nop 0
	v_writelane_b32 v250, s1, 27
	s_lshl_b64 s[0:1], s[2:3], 16
	s_add_u32 s0, s92, s0
	s_addc_u32 s1, s93, s1
	v_readlane_b32 s18, v250, 23
	s_branch .LBB0_113

; DI void attn_item_A(const Params& p, int layer, int b, int head, int qb, u16* sm, float lam, float lam_init, int wv) {
;     ...
;   const int npairs = (qb >> 1) + 1;
;   const int T0 = 2 * (npairs - 1) + kh;
;   const bool v0 = (T0 <= qb);
;   auto dma_tile = [&](int T, int c) {
;     const int k0 = 64 * T;
;     u16* Kd = Kb0 + c * (2 * 64 * 64) + wp * (8 * 64);
; #pragma unroll
;     for (int i = 0; i < 4; ++i) {
;       __builtin_amdgcn_global_load_lds((const unsigned*)(kg + (size_t)(k0 + row0 + 16 * i) * DIN), (unsigned*)(Kd + i * 16 * 64), 16, 0, 0);
;       __builtin_amdgcn_global_load_lds((const unsigned*)(vg + (size_t)(row0 + 16 * i) * SEQ + k0), (unsigned*)(Kd + 64 * 64 + i * 16 * 64), 16, 0, 0);
;     }
;   };
;   if (v0) dma_tile(T0, 0);
;   asm volatile("" :: "v"(qf[0]), "v"(qf[1]), "v"(qf[2]), "v"(qf[3]));
;   asm volatile("s_waitcnt vmcnt(0)" ::: "memory");
;   __syncthreads();
;   for (int j = 0; j < npairs; ++j) {
;     if (j + 1 < npairs) dma_tile(T0 - 2 * (j + 1), (j + 1) & 1);
;     if (j > 0 || v0) {
;       const int T = T0 - 2 * j;
;       const u16* Ks = Kb0 + (j & 1) * (2 * 64 * 64);
;       const u16* Vs = Ks + 64 * 64;
;       const int k0 = 64 * T;
;       const bool need_mask = (T == qb);
;       const int dl = qpos - k0 - 4 * h;
;       diff_softmax_pv(qf, Ks, Vs, m0, ls0, ls1, ones, o, sl2, dl, need_mask, !started, r, h, 64, lo);
.LBB0_276:
	s_or_b64 exec, exec, s[18:19]
	s_waitcnt vmcnt(0)
	v_and_b32_e32 v205, 60, v125
	s_waitcnt vmcnt(0) lgkmcnt(0)
	s_barrier
	s_and_saveexec_b64 s[18:19], vcc
	s_cbranch_execz .LBB0_292
	v_add_u32_e32 v66, v120, v171
	v_sub_u32_e32 v66, v66, v124
	v_lshlrev_b32_e32 v67, 6, v118
	v_sub_u32_e32 v66, v66, v67
	v_lshlrev_b32_e32 v206, 6, v173
	v_lshlrev_b32_e32 v67, 6, v119
	v_sub_u32_e32 v66, v66, v206
	v_and_b32_e32 v67, 0xffffff80, v67
	v_sub_u32_e32 v66, v66, v67
	v_add_u32_e32 v207, 0x2040, v66
	v_add_u32_e32 v66, v118, v173
	s_movk_i32 s2, 0xff7f
	v_add3_u32 v208, v66, v123, s2
	v_or_b32_e32 v66, v121, v67
	v_cmp_gt_u32_e64 s[36:37], 16, v171
	v_add_u32_e32 v209, v66, v122
	v_add_u32_e32 v210, 0xffffff00, v67
	v_add_u32_e32 v72, v206, v209
	v_add_u32_e32 v68, 0xffffff00, v72
	v_mad_i64_i32 v[68:69], s[38:39], v68, s8, v[160:161]
	v_readlane_b32 s22, v250, 19
	v_add_u32_e32 v66, v206, v210
	v_ashrrev_i32_e32 v67, 31, v66
	v_lshl_add_u64 v[68:69], v[68:69], 0, s[68:69]
	v_lshlrev_b64 v[66:67], 1, v[66:67]
	v_or_b32_e32 v74, v121, v122
	v_subrev_u32_e32 v75, s22, v160
	v_lshl_add_u64 v[70:71], v[162:163], 0, v[66:67]
	v_mul_u32_u24_e32 v76, 0x1a00, v74
	v_lshlrev_b32_e32 v77, 14, v74
	v_add_u32_e32 v76, v76, v75
	v_add_u32_e32 v77, v77, v75
	v_sub_co_u32_e32 v68, vcc, v68, v76
	s_nop 1
	v_subbrev_co_u32_e32 v69, vcc, 0, v69, vcc
	v_sub_co_u32_e32 v70, vcc, v70, v77
	s_nop 1
	v_subbrev_co_u32_e32 v71, vcc, 0, v71, vcc
	v_mov_b32_e32 v160, v76
	v_readfirstlane_b32 s98, v68
	v_readfirstlane_b32 s99, v69
	v_readfirstlane_b32 s100, v70
	v_readfirstlane_b32 s101, v71
	v_readfirstlane_b32 s87, v177
	v_add_u32_e32 v161, 0x1a000, v76
	v_add_u32_e32 v162, 0x34000, v76
	v_add_u32_e32 v163, 0x4e000, v76
	v_mov_b32_e32 v164, v77
	v_add_u32_e32 v165, 0x40000, v77
	v_add_u32_e32 v166, 0x80000, v77
	v_add_u32_e32 v167, 0xc0000, v77
	s_movk_i32 s64, 0x2000
	s_mov_b32 s65, 0
	s_mov_b64 s[40:41], 0
	s_mov_b64 s[42:43], s[4:5]
	s_getreg_b32 s22, hwreg(HW_REG_HW_ID, 0, 1)
	s_cmp_eq_u32 s22, 1
	s_cbranch_scc0 .LBB0_279
	s_setprio 0
	s_branch .LBB0_279_H
	s_nop 0
	s_nop 0
	s_nop 0
	s_nop 0
	s_nop 0
	s_nop 0
	s_nop 0
	s_nop 0
	s_nop 0
	s_nop 0
	s_nop 0
	s_nop 0
	s_nop 0

; DI float ex2(float x) { return __builtin_amdgcn_exp2f(x); }
; DI f32x16 mfma(bf16x8 a, bf16x8 b, f32x16 c) { return __builtin_amdgcn_mfma_f32_32x32x16_bf16(a, b, c, 0, 0, 0); }
; DI f32x4 mfma16(bf16x8 a, bf16x8 b, f32x4 c) { return __builtin_amdgcn_mfma_f32_16x16x32_bf16(a, b, c, 0, 0, 0); }
; DI void pv_frag_step(f32x16& s0, f32x16& s1, const u16* Vs, f32x16& o0, f32x16& o1, f32x4& ls, bf16x8 ones, int rs, const int (&lo)[4]) {
; #pragma unroll
;   for (int i = 0; i < 16; ++i) { s0[i] = ex2(s0[i]); s1[i] = ex2(s1[i]); }
; #pragma unroll
;   for (int kk = 0; kk < 4; ++kk) {
;     const int s = kk & 1;
;     unsigned u0, u1, u2, u3;
;     if (kk < 2) {
;       u0 = pk2(s0[8 * s], s0[8 * s + 1]); u1 = pk2(s0[8 * s + 2], s0[8 * s + 3]);
;       u2 = pk2(s0[8 * s + 4], s0[8 * s + 5]); u3 = pk2(s0[8 * s + 6], s0[8 * s + 7]);
;     } else {
;       u0 = pk2(s1[8 * s], s1[8 * s + 1]); u1 = pk2(s1[8 * s + 2], s1[8 * s + 3]);
;       u2 = pk2(s1[8 * s + 4], s1[8 * s + 5]); u3 = pk2(s1[8 * s + 6], s1[8 * s + 7]);
;     }
;     u32x4 uu = {u0, u1, u2, u3};
;     bf16x8 pf = __builtin_bit_cast(bf16x8, uu);
;     bf16x8 v0 = ldsv(Vs + lo[kk]);
;     bf16x8 v1 = ldsv(Vs + 32 * rs + lo[kk]);
;     o0 = mfma(v0, pf, o0);
;     o1 = mfma(v1, pf, o1);
;     ls = mfma16(ones, pf, ls);
;   }
; }
; DI void diff_softmax_pv(const bf16x8 (&qf)[4], const u16* Ks, const u16* Vs, float& m, f32x4& ls0, f32x4& ls1, bf16x8 ones,
;                         f32x16 (&o)[2][2], float sl2, int dl, bool need_mask, bool first, int r, int h, int rs, const int (&lo)[4]) {
;     ...
;     pv_frag_step(s0, s1, Vs, o[0][0], o[0][1], ls0, ones, rs, lo);
;   }
;   {
;     f32x16 s0 = mfma(ldsv(Ks + lo[2]), qf[2], b0);
;     f32x16 s1 = mfma(ldsv(Ks + 32 * rs + lo[2]), qf[2], b1);
;     s0 = mfma(ldsv(Ks + lo[3]), qf[3], s0);
;     s1 = mfma(ldsv(Ks + 32 * rs + lo[3]), qf[3], s1);
;     if (need_mask) mask_causal(s0, s1, dl);
;     pv_frag_step(s0, s1, Vs, o[1][0], o[1][1], ls1, ones, rs, lo);
.LBB0_289:
	v_exp_f32_e32 v98, v98
	v_exp_f32_e32 v99, v99
	v_exp_f32_e32 v100, v100
	v_exp_f32_e32 v101, v101
	v_exp_f32_e32 v102, v102
	v_exp_f32_e32 v103, v103
	v_exp_f32_e32 v104, v104
	v_exp_f32_e32 v105, v105
	v_exp_f32_e32 v218, v118
	v_exp_f32_e32 v219, v119
	v_exp_f32_e32 v220, v120
	v_exp_f32_e32 v221, v121
	v_exp_f32_e32 v118, v106
	v_exp_f32_e32 v119, v107
	v_exp_f32_e32 v120, v108
	v_exp_f32_e32 v121, v109
	v_cvt_pk_bf16_f32 v106, v98, v99
	v_cvt_pk_bf16_f32 v107, v100, v101
	v_cvt_pk_bf16_f32 v109, v104, v105
	v_cvt_pk_bf16_f32 v108, v102, v103
	ds_read_b128 v[98:101], v213 offset:8192
	ds_read_b128 v[102:105], v213 offset:12288
	v_exp_f32_e32 v110, v110
	v_exp_f32_e32 v111, v111
	v_exp_f32_e32 v112, v112
	v_exp_f32_e32 v113, v113
	s_waitcnt lgkmcnt(1)
	v_mfma_f32_32x32x16_bf16 v[2:17], v[98:101], v[106:109], v[2:17]
	v_exp_f32_e32 v214, v114
	v_exp_f32_e32 v215, v115
	v_exp_f32_e32 v216, v116
	v_exp_f32_e32 v217, v117
	v_cvt_pk_bf16_f32 v118, v118, v119
	v_cvt_pk_bf16_f32 v119, v120, v121
	v_cvt_pk_bf16_f32 v121, v112, v113
	s_waitcnt lgkmcnt(0)
	v_mfma_f32_32x32x16_bf16 v[34:49], v[102:105], v[106:109], v[34:49]
	v_cvt_pk_bf16_f32 v120, v110, v111
	v_exp_f32_e32 v227, v127
	v_cvt_pk_bf16_f32 v127, v216, v217
	v_lshl_add_u32 v216, v185, 1, v211
	v_exp_f32_e32 v222, v122
	v_exp_f32_e32 v223, v123
	v_exp_f32_e32 v224, v124
	v_mfma_f32_16x16x32_bf16 v[114:117], v[146:149], v[106:109], v[150:153]
	ds_read_b128 v[106:109], v212 offset:8192
	ds_read_b128 v[110:113], v212 offset:12288
	v_exp_f32_e32 v225, v125
	v_exp_f32_e32 v226, v126
	s_waitcnt lgkmcnt(1)
	v_mfma_f32_32x32x16_bf16 v[2:17], v[106:109], v[118:121], v[2:17]
	v_exp_f32_e32 v228, v128
	v_exp_f32_e32 v229, v129
	v_cvt_pk_bf16_f32 v126, v214, v215
	v_cvt_pk_bf16_f32 v129, v220, v221
	v_cvt_pk_bf16_f32 v128, v218, v219
	v_lshl_add_u32 v211, v186, 1, v211
	v_cvt_pk_bf16_f32 v212, v222, v223
	s_waitcnt lgkmcnt(0)
	v_mfma_f32_32x32x16_bf16 v[34:49], v[110:113], v[118:121], v[34:49]
	v_cvt_pk_bf16_f32 v213, v224, v225
	v_cvt_pk_bf16_f32 v215, v228, v229
	v_cvt_pk_bf16_f32 v214, v226, v227
	v_mfma_f32_16x16x32_bf16 v[122:125], v[146:149], v[118:121], v[114:117]
	s_nop 2
	ds_read_b128 v[114:117], v216 offset:8192
	ds_read_b128 v[118:121], v216 offset:12288
	s_waitcnt lgkmcnt(1)
	v_mfma_f32_32x32x16_bf16 v[2:17], v[114:117], v[126:129], v[2:17]
	s_waitcnt lgkmcnt(0)
	v_mfma_f32_32x32x16_bf16 v[34:49], v[118:121], v[126:129], v[34:49]
	v_mfma_f32_16x16x32_bf16 v[150:153], v[146:149], v[126:129], v[122:125]
	s_nop 2
	ds_read_b128 v[122:125], v211 offset:8192
	ds_read_b128 v[126:129], v211 offset:12288
	s_waitcnt lgkmcnt(1)
	v_mfma_f32_32x32x16_bf16 v[2:17], v[122:125], v[212:215], v[2:17]
	s_waitcnt lgkmcnt(0)
	v_mfma_f32_32x32x16_bf16 v[34:49], v[126:129], v[212:215], v[34:49]
	v_mfma_f32_16x16x32_bf16 v[150:153], v[146:149], v[212:215], v[150:153]
	v_mfma_f32_32x32x16_bf16 v[66:81], v[230:233], v[138:141], v[66:81]
	v_mfma_f32_32x32x16_bf16 v[82:97], v[234:237], v[138:141], v[82:97]
	v_mfma_f32_32x32x16_bf16 v[66:81], v[238:241], v[142:145], v[66:81]
	v_mfma_f32_32x32x16_bf16 v[82:97], v[242:245], v[142:145], v[82:97]
	s_and_saveexec_b64 s[2:3], s[38:39]
	s_cbranch_execz .LBB0_278
	v_cmp_lt_i32_e32 vcc, -1, v207
	s_nop 7
	v_cndmask_b32_e32 v66, v199, v66, vcc
	v_cmp_lt_i32_e32 vcc, 31, v207
	s_nop 1
	v_cndmask_b32_e32 v82, v199, v82, vcc
	v_cmp_lt_i32_e32 vcc, 0, v207
	s_nop 1
	v_cndmask_b32_e32 v67, v199, v67, vcc
	v_cmp_lt_i32_e32 vcc, 32, v207
	s_nop 1
	v_cndmask_b32_e32 v83, v199, v83, vcc
	v_cmp_lt_i32_e32 vcc, 1, v207
	s_nop 1
	v_cndmask_b32_e32 v68, v199, v68, vcc
	v_cmp_lt_i32_e32 vcc, 33, v207
	s_nop 1
	v_cndmask_b32_e32 v84, v199, v84, vcc
	v_cmp_lt_i32_e32 vcc, 2, v207
	s_nop 1
	v_cndmask_b32_e32 v69, v199, v69, vcc
	v_cmp_lt_i32_e32 vcc, 34, v207
	s_nop 1
	v_cndmask_b32_e32 v85, v199, v85, vcc
	v_cmp_lt_i32_e32 vcc, 7, v207
	s_nop 1
	v_cndmask_b32_e32 v70, v199, v70, vcc
	v_cmp_lt_i32_e32 vcc, 39, v207
	s_nop 1
	v_cndmask_b32_e32 v86, v199, v86, vcc
	v_cmp_lt_i32_e32 vcc, 8, v207
	s_nop 1
	v_cndmask_b32_e32 v71, v199, v71, vcc
	v_cmp_lt_i32_e32 vcc, 40, v207
	s_nop 1
	v_cndmask_b32_e32 v87, v199, v87, vcc
	v_cmp_lt_i32_e32 vcc, 9, v207
	s_nop 1
	v_cndmask_b32_e32 v72, v199, v72, vcc
	v_cmp_lt_i32_e32 vcc, 41, v207
	s_nop 1
	v_cndmask_b32_e32 v88, v199, v88, vcc
	v_cmp_lt_i32_e32 vcc, 10, v207
	s_nop 1
	v_cndmask_b32_e32 v73, v199, v73, vcc
	v_cmp_lt_i32_e32 vcc, 42, v207
	s_nop 1
	v_cndmask_b32_e32 v89, v199, v89, vcc
	v_cmp_lt_i32_e32 vcc, 15, v207
	s_nop 1
	v_cndmask_b32_e32 v74, v199, v74, vcc
	v_cmp_lt_i32_e32 vcc, 47, v207
	s_nop 1
	v_cndmask_b32_e32 v90, v199, v90, vcc
	v_cmp_lt_i32_e32 vcc, 16, v207
	s_nop 1
	v_cndmask_b32_e32 v75, v199, v75, vcc
	v_cmp_lt_i32_e32 vcc, 48, v207
	s_nop 1
	v_cndmask_b32_e32 v91, v199, v91, vcc
	v_cmp_lt_i32_e32 vcc, 17, v207
	s_nop 1
	v_cndmask_b32_e32 v76, v199, v76, vcc
	v_cmp_lt_i32_e32 vcc, 49, v207
	s_nop 1
	v_cndmask_b32_e32 v92, v199, v92, vcc
	v_cmp_lt_i32_e32 vcc, 18, v207
	s_nop 1
	v_cndmask_b32_e32 v77, v199, v77, vcc
	v_cmp_lt_i32_e32 vcc, 50, v207
	s_nop 1
	v_cndmask_b32_e32 v93, v199, v93, vcc
	v_cmp_lt_i32_e32 vcc, 23, v207
	s_nop 1
	v_cndmask_b32_e32 v78, v199, v78, vcc
	v_cmp_lt_i32_e32 vcc, 55, v207
	s_nop 1
	v_cndmask_b32_e32 v94, v199, v94, vcc
	v_cmp_lt_i32_e32 vcc, 24, v207
	s_nop 1
	v_cndmask_b32_e32 v79, v199, v79, vcc
	v_cmp_lt_i32_e32 vcc, 56, v207
	s_nop 1
	v_cndmask_b32_e32 v95, v199, v95, vcc
	v_cmp_lt_i32_e32 vcc, 25, v207
	s_nop 1
	v_cndmask_b32_e32 v80, v199, v80, vcc
	v_cmp_lt_i32_e32 vcc, 57, v207
	s_nop 1
	v_cndmask_b32_e32 v96, v199, v96, vcc
	v_cmp_lt_i32_e32 vcc, 26, v207
	s_nop 1
	v_cndmask_b32_e32 v81, v199, v81, vcc
	v_cmp_lt_i32_e32 vcc, 58, v207
	s_nop 1
	v_cndmask_b32_e32 v97, v199, v97, vcc
	s_branch .LBB0_278
	s_nop 0
	s_nop 0
	s_nop 0
	s_nop 0

; DI f32x16 mfma(bf16x8 a, bf16x8 b, f32x16 c) { return __builtin_amdgcn_mfma_f32_32x32x16_bf16(a, b, c, 0, 0, 0); }
; DI void mask_causal(f32x16& s0, f32x16& s1, int dl) {
; #pragma unroll
;   for (int i = 0; i < 16; ++i) {
;     const int ci = (i & 3) + 8 * (i >> 2);
;     s0[i] = (ci <= dl) ? s0[i] : -INFINITY;
;     s1[i] = (ci + 32 <= dl) ? s1[i] : -INFINITY;
;   }
; }
; DI void diff_softmax_pv(const bf16x8 (&qf)[4], const u16* Ks, const u16* Vs, float& m, f32x4& ls0, f32x4& ls1, bf16x8 ones,
;                         f32x16 (&o)[2][2], float sl2, int dl, bool need_mask, bool first, int r, int h, int rs, const int (&lo)[4]) {
;     ...
;   const float nb = -sl2 * (float)dl - m;
; #pragma unroll
;   for (int i = 0; i < 16; ++i) {
;     const int ci = (i & 3) + 8 * (i >> 2);
;     b0[i] = fmaf(sl2, (float)ci, nb);
;     b1[i] = fmaf(sl2, (float)(ci + 32), nb);
;   }
;   {
;     __builtin_amdgcn_s_setprio(1);
;     f32x16 s0 = mfma(ldsv(Ks + lo[0]), qf[0], b0);
;     f32x16 s1 = mfma(ldsv(Ks + 32 * rs + lo[0]), qf[0], b1);
;     s0 = mfma(ldsv(Ks + lo[1]), qf[1], s0);
;     s1 = mfma(ldsv(Ks + 32 * rs + lo[1]), qf[1], s1);
;     __builtin_amdgcn_s_setprio(0);
;     if (need_mask) mask_causal(s0, s1, dl);
.LBB0_281_H:
	s_or_b64 exec, exec, s[2:3]
	v_cvt_f32_i32_e32 v66, v207
	s_and_b32 s2, s64, 0x2000
	v_lshl_add_u32 v211, s2, 1, v176
	v_lshl_add_u32 v213, v183, 1, v211
	v_lshl_add_u32 v212, v184, 1, v211
	v_fma_f32 v229, -v178, v66, -v204
	v_lshl_add_u32 v246, v185, 1, v211
	v_lshl_add_u32 v247, v186, 1, v211
	ds_read_b128 v[114:117], v213
	ds_read_b128 v[214:217], v213 offset:4096
	ds_read_b128 v[218:221], v212
	ds_read_b128 v[222:225], v212 offset:4096
	ds_read_b128 v[230:233], v246
	ds_read_b128 v[234:237], v246 offset:4096
	ds_read_b128 v[238:241], v247
	ds_read_b128 v[242:245], v247 offset:4096
	v_cmp_eq_u32_e64 s[38:39], 0, v208
	v_fma_f32 v66, 0, v178, v229
	v_add_f32_e32 v67, v178, v229
	v_fmamk_f32 v68, v178, 0x40000000, v229
	v_fmamk_f32 v69, v178, 0x40400000, v229
	v_fmamk_f32 v70, v178, 0x41000000, v229
	v_fmamk_f32 v71, v178, 0x41100000, v229
	v_fmamk_f32 v72, v178, 0x41200000, v229
	v_fmamk_f32 v73, v178, 0x41300000, v229
	v_fmamk_f32 v74, v178, 0x41800000, v229
	v_fmamk_f32 v75, v178, 0x41880000, v229
	v_fmamk_f32 v76, v178, 0x41900000, v229
	v_fmamk_f32 v77, v178, 0x41980000, v229
	v_fmamk_f32 v78, v178, 0x41c00000, v229
	v_fmamk_f32 v79, v178, 0x41c80000, v229
	v_fmamk_f32 v80, v178, 0x41d00000, v229
	v_fmamk_f32 v81, v178, 0x41d80000, v229
	v_fmamk_f32 v82, v178, 0x42000000, v229
	v_fmamk_f32 v83, v178, 0x42040000, v229
	v_fmamk_f32 v84, v178, 0x42080000, v229
	v_fmamk_f32 v85, v178, 0x420c0000, v229
	v_fmamk_f32 v86, v178, 0x42200000, v229
	v_fmamk_f32 v87, v178, 0x42240000, v229
	v_fmamk_f32 v88, v178, 0x42280000, v229
	v_fmamk_f32 v89, v178, 0x422c0000, v229
	v_fmamk_f32 v90, v178, 0x42400000, v229
	v_fmamk_f32 v91, v178, 0x42440000, v229
	v_fmamk_f32 v92, v178, 0x42480000, v229
	v_fmamk_f32 v93, v178, 0x424c0000, v229
	v_fmamk_f32 v94, v178, 0x42600000, v229
	v_fmamk_f32 v95, v178, 0x42640000, v229
	v_fmamk_f32 v96, v178, 0x42680000, v229
	v_fmamk_f32 v97, v178, 0x426c0000, v229
	s_setprio 2
	s_waitcnt lgkmcnt(6)
	v_mfma_f32_32x32x16_bf16 v[98:113], v[114:117], v[130:133], v[66:81]
	v_mfma_f32_32x32x16_bf16 v[114:129], v[214:217], v[130:133], v[82:97]
	s_waitcnt lgkmcnt(5)
	v_mfma_f32_32x32x16_bf16 v[98:113], v[218:221], v[134:137], v[98:113]
	s_waitcnt lgkmcnt(4)
	v_mfma_f32_32x32x16_bf16 v[114:129], v[222:225], v[134:137], v[114:129]
	s_setprio 0
	s_and_saveexec_b64 s[2:3], s[38:39]
	s_cbranch_execz .LBB0_283_H
	v_cmp_lt_i32_e32 vcc, -1, v207
	s_nop 5
	v_cndmask_b32_e32 v98, v199, v98, vcc
	v_cmp_lt_i32_e32 vcc, 31, v207
	s_nop 1
	v_cndmask_b32_e32 v114, v199, v114, vcc
	v_cmp_lt_i32_e32 vcc, 0, v207
	s_nop 1
	v_cndmask_b32_e32 v99, v199, v99, vcc
	v_cmp_lt_i32_e32 vcc, 32, v207
	s_nop 1
	v_cndmask_b32_e32 v115, v199, v115, vcc
	v_cmp_lt_i32_e32 vcc, 1, v207
	s_nop 1
	v_cndmask_b32_e32 v100, v199, v100, vcc
	v_cmp_lt_i32_e32 vcc, 33, v207
	s_nop 1
	v_cndmask_b32_e32 v116, v199, v116, vcc
	v_cmp_lt_i32_e32 vcc, 2, v207
	s_nop 1
	v_cndmask_b32_e32 v101, v199, v101, vcc
	v_cmp_lt_i32_e32 vcc, 34, v207
	s_nop 1
	v_cndmask_b32_e32 v117, v199, v117, vcc
	v_cmp_lt_i32_e32 vcc, 7, v207
	s_nop 1
	v_cndmask_b32_e32 v102, v199, v102, vcc
	v_cmp_lt_i32_e32 vcc, 39, v207
	s_nop 1
	v_cndmask_b32_e32 v118, v199, v118, vcc
	v_cmp_lt_i32_e32 vcc, 8, v207
	s_nop 1
	v_cndmask_b32_e32 v103, v199, v103, vcc
	v_cmp_lt_i32_e32 vcc, 40, v207
	s_nop 1
	v_cndmask_b32_e32 v119, v199, v119, vcc
	v_cmp_lt_i32_e32 vcc, 9, v207
	s_nop 1
	v_cndmask_b32_e32 v104, v199, v104, vcc
	v_cmp_lt_i32_e32 vcc, 41, v207
	s_nop 1
	v_cndmask_b32_e32 v120, v199, v120, vcc
	v_cmp_lt_i32_e32 vcc, 10, v207
	s_nop 1
	v_cndmask_b32_e32 v105, v199, v105, vcc
	v_cmp_lt_i32_e32 vcc, 42, v207
	s_nop 1
	v_cndmask_b32_e32 v121, v199, v121, vcc
	v_cmp_lt_i32_e32 vcc, 15, v207
	s_nop 1
	v_cndmask_b32_e32 v106, v199, v106, vcc
	v_cmp_lt_i32_e32 vcc, 47, v207
	s_nop 1
	v_cndmask_b32_e32 v122, v199, v122, vcc
	v_cmp_lt_i32_e32 vcc, 16, v207
	s_nop 1
	v_cndmask_b32_e32 v107, v199, v107, vcc
	v_cmp_lt_i32_e32 vcc, 48, v207
	s_nop 1
	v_cndmask_b32_e32 v123, v199, v123, vcc
	v_cmp_lt_i32_e32 vcc, 17, v207
	s_nop 1
	v_cndmask_b32_e32 v108, v199, v108, vcc
	v_cmp_lt_i32_e32 vcc, 49, v207
	s_nop 1
	v_cndmask_b32_e32 v124, v199, v124, vcc
	v_cmp_lt_i32_e32 vcc, 18, v207
	s_nop 1
	v_cndmask_b32_e32 v109, v199, v109, vcc
	v_cmp_lt_i32_e32 vcc, 50, v207
	s_nop 1
	v_cndmask_b32_e32 v125, v199, v125, vcc
	v_cmp_lt_i32_e32 vcc, 23, v207
	s_nop 1
	v_cndmask_b32_e32 v110, v199, v110, vcc
	v_cmp_lt_i32_e32 vcc, 55, v207
	s_nop 1
	v_cndmask_b32_e32 v126, v199, v126, vcc
	v_cmp_lt_i32_e32 vcc, 24, v207
	s_nop 1
	v_cndmask_b32_e32 v111, v199, v111, vcc
	v_cmp_lt_i32_e32 vcc, 56, v207
	s_nop 1
	v_cndmask_b32_e32 v127, v199, v127, vcc
	v_cmp_lt_i32_e32 vcc, 25, v207
	s_nop 1
	v_cndmask_b32_e32 v112, v199, v112, vcc
	v_cmp_lt_i32_e32 vcc, 57, v207
	s_nop 1
	v_cndmask_b32_e32 v128, v199, v128, vcc
	v_cmp_lt_i32_e32 vcc, 26, v207
	s_nop 1
	v_cndmask_b32_e32 v113, v199, v113, vcc
	v_cmp_lt_i32_e32 vcc, 58, v207
	s_nop 1
	v_cndmask_b32_e32 v129, v199, v129, vcc

; DI void attn_item_A(const Params& p, int layer, int b, int head, int qb, u16* sm, float lam, float lam_init, int wv) {
;     ...
;   for (int j = 0; j < npairs; ++j) {
;     if (j + 1 < npairs) dma_tile(T0 - 2 * (j + 1), (j + 1) & 1);
;     if (j > 0 || v0) {
;       const int T = T0 - 2 * j;
;       const u16* Ks = Kb0 + (j & 1) * (2 * 64 * 64);
;       const u16* Vs = Ks + 64 * 64;
;       const int k0 = 64 * T;
;       const bool need_mask = (T == qb);
;       const int dl = qpos - k0 - 4 * h;
;       diff_softmax_pv(qf, Ks, Vs, m0, ls0, ls1, ones, o, sl2, dl, need_mask, !started, r, h, 64, lo);
;       m1 = m0;
;       started = true;
;     }
;     asm volatile("s_waitcnt vmcnt(0)" ::: "memory");
;     __syncthreads();
;   }
;   if (!started) { m0 = -INFINITY; m1 = -INFINITY; }
.LBB0_291:
	s_setprio 0
	s_or_b64 exec, exec, s[40:41]
	s_or_b64 s[4:5], s[4:5], exec
	v_readlane_b32 s41, v250, 28

; __global__ void __launch_bounds__(256, 2) hymba_mega(Params p) {
;     ...
;     xcd_barrier(gb);
;     for (int u = lb; u < 8 * 8; u += nxb) gemm_tile<1>(p, layer, xcd + 8 * (u & 7), u >> 3, sm, wv);
;     xcd_barrier(gb);
.LBB0_392:
	s_or_b64 exec, exec, s[0:1]
	v_readlane_b32 s0, v250, 24
	v_readlane_b32 s1, v250, 25
	s_andn2_b64 vcc, exec, s[0:1]
	s_waitcnt lgkmcnt(0)
	s_barrier
	s_cbranch_vccnz .LBB0_471
	v_readlane_b32 s2, v250, 23
	s_cmp_lt_u32 s2, 32
	s_cbranch_scc1 .Lstag_o
	s_sleep 12
.Lstag_o:
	v_readlane_b32 s0, v250, 26
	s_mov_b32 s2, s0
	s_lshl_b32 s0, s0, 21
	v_readlane_b32 s1, v250, 27
	s_add_u32 s6, s58, s0
	s_addc_u32 s7, s59, 0
	s_mov_b32 s1, s25
	s_lshl_b32 s0, s2, 14
	s_lshl_b64 s[0:1], s[0:1], 2
	s_add_u32 s0, s92, s0
	s_addc_u32 s1, s93, s1
	s_add_u32 s0, s0, 0x10000
	s_addc_u32 s1, s1, 0
	v_readlane_b32 s16, v250, 23
	s_branch .LBB0_395
